# global seams 0-4,6: non-leaders poll the cross-XCD release word directly; dattn V loads issued right behind the K loads
# baseline (speedup 1.0000x reference)
.LBB0_343:
	s_or_b64 exec, exec, s[6:7]
	v_cvt_f32_u32_e32 v4, v2
	s_waitcnt vmcnt(0)
	v_readfirstlane_b32 s4, v3
	v_sub_u32_e32 v3, 0, v2
	v_rcp_iflag_f32_e32 v4, v4
	v_add_u32_e32 v5, s4, v1
	v_mul_f32_e32 v4, 0x4f7ffffe, v4
	v_cvt_u32_f32_e32 v4, v4
	v_mul_lo_u32 v1, v3, v4
	v_mul_hi_u32 v1, v4, v1
	v_add_u32_e32 v1, v4, v1
	v_mul_hi_u32 v1, v5, v1
	v_mul_lo_u32 v3, v1, v2
	v_sub_u32_e32 v3, v5, v3
	v_add_u32_e32 v4, 1, v1
	v_cmp_ge_u32_e32 vcc, v3, v2
	s_nop 1
	v_cndmask_b32_e32 v1, v1, v4, vcc
	v_sub_u32_e32 v4, v3, v2
	v_cndmask_b32_e32 v3, v3, v4, vcc
	v_add_u32_e32 v4, 1, v1
	v_cmp_ge_u32_e32 vcc, v3, v2
	v_add_u32_e32 v3, 1, v5
	s_nop 0
	v_cndmask_b32_e32 v1, v1, v4, vcc
	v_mul_lo_u32 v4, v2, v1
	v_add_u32_e32 v2, v4, v2
	v_cmp_ne_u32_e32 vcc, v3, v2
	s_and_saveexec_b64 s[4:5], vcc
	s_xor_b64 s[4:5], exec, s[4:5]
	s_cbranch_execz .LBB0_357
	s_waitcnt lgkmcnt(0)
	v_readlane_b32 s10, v244, 6
	v_readlane_b32 s11, v244, 7
	v_mov_b32_e32 v0, 0
	s_add_u32 s10, s10, 0x1fd03500
	s_addc_u32 s11, s11, 0
	v_mov_b32_e32 v1, 0
	s_nop 0
	global_load_dword v0, v0, s[10:11] sc1
	s_waitcnt vmcnt(0)
	v_cmp_eq_u32_e32 vcc, v0, v1
	s_and_saveexec_b64 s[6:7], vcc
	s_cbranch_execz .LBB0_356
	v_readlane_b32 s24, v244, 0
	v_readlane_b32 s28, v244, 4
	v_readlane_b32 s29, v244, 5
	v_readlane_b32 s30, v244, 6
	v_readlane_b32 s31, v244, 7
	s_mov_b64 s[12:13], s[28:29]
	s_mov_b64 s[14:15], s[30:31]
	s_add_u32 s8, s14, 0x1fd00200
	s_addc_u32 s9, s15, 0
	s_mov_b32 s28, 1
	s_mov_b64 s[12:13], 0
	v_mov_b32_e32 v0, 0
	v_readlane_b32 s25, v244, 1
	v_readlane_b32 s26, v244, 2
	v_readlane_b32 s27, v244, 3
	s_branch .LBB0_347

.LBB0_472:
	s_or_b64 exec, exec, s[8:9]
	v_cvt_f32_u32_e32 v4, v2
	s_waitcnt vmcnt(0)
	v_readfirstlane_b32 s6, v3
	v_sub_u32_e32 v3, 0, v2
	v_rcp_iflag_f32_e32 v4, v4
	v_add_u32_e32 v5, s6, v1
	v_mul_f32_e32 v4, 0x4f7ffffe, v4
	v_cvt_u32_f32_e32 v4, v4
	v_mul_lo_u32 v1, v3, v4
	v_mul_hi_u32 v1, v4, v1
	v_add_u32_e32 v1, v4, v1
	v_mul_hi_u32 v1, v5, v1
	v_mul_lo_u32 v3, v1, v2
	v_sub_u32_e32 v3, v5, v3
	v_add_u32_e32 v4, 1, v1
	v_cmp_ge_u32_e32 vcc, v3, v2
	s_nop 1
	v_cndmask_b32_e32 v1, v1, v4, vcc
	v_sub_u32_e32 v4, v3, v2
	v_cndmask_b32_e32 v3, v3, v4, vcc
	v_add_u32_e32 v4, 1, v1
	v_cmp_ge_u32_e32 vcc, v3, v2
	v_add_u32_e32 v3, 1, v5
	s_nop 0
	v_cndmask_b32_e32 v1, v1, v4, vcc
	v_mul_lo_u32 v4, v2, v1
	v_add_u32_e32 v2, v4, v2
	v_cmp_ne_u32_e32 vcc, v3, v2
	s_and_saveexec_b64 s[6:7], vcc
	s_xor_b64 s[6:7], exec, s[6:7]
	s_cbranch_execz .LBB0_486
	s_waitcnt lgkmcnt(0)
	v_readlane_b32 s12, v244, 6
	v_readlane_b32 s13, v244, 7
	v_mov_b32_e32 v0, 0
	s_add_u32 s12, s12, 0x1fd03500
	s_addc_u32 s13, s13, 0
	v_mov_b32_e32 v1, 1
	s_nop 0
	global_load_dword v0, v0, s[12:13] sc1
	s_waitcnt vmcnt(0)
	v_cmp_eq_u32_e32 vcc, v0, v1
	s_and_saveexec_b64 s[8:9], vcc
	s_cbranch_execz .LBB0_485
	v_readlane_b32 s24, v244, 0
	v_readlane_b32 s28, v244, 4
	v_readlane_b32 s29, v244, 5
	v_readlane_b32 s30, v244, 6
	v_readlane_b32 s31, v244, 7
	s_mov_b64 s[16:17], s[28:29]
	s_mov_b64 s[18:19], s[30:31]
	s_add_u32 s10, s18, 0x1fd00200
	s_addc_u32 s11, s19, 0
	s_mov_b32 s28, 1
	s_mov_b64 s[14:15], 0
	v_mov_b32_e32 v0, 0
	v_readlane_b32 s25, v244, 1
	v_readlane_b32 s26, v244, 2
	v_readlane_b32 s27, v244, 3
	s_branch .LBB0_476

.LBB0_1341:
	s_or_b64 exec, exec, s[8:9]
	v_cvt_f32_u32_e32 v4, v2
	s_waitcnt vmcnt(0)
	v_readfirstlane_b32 s6, v3
	v_sub_u32_e32 v3, 0, v2
	v_rcp_iflag_f32_e32 v4, v4
	v_add_u32_e32 v5, s6, v1
	v_mul_f32_e32 v4, 0x4f7ffffe, v4
	v_cvt_u32_f32_e32 v4, v4
	v_mul_lo_u32 v1, v3, v4
	v_mul_hi_u32 v1, v4, v1
	v_add_u32_e32 v1, v4, v1
	v_mul_hi_u32 v1, v5, v1
	v_mul_lo_u32 v3, v1, v2
	v_sub_u32_e32 v3, v5, v3
	v_add_u32_e32 v4, 1, v1
	v_cmp_ge_u32_e32 vcc, v3, v2
	s_nop 1
	v_cndmask_b32_e32 v1, v1, v4, vcc
	v_sub_u32_e32 v4, v3, v2
	v_cndmask_b32_e32 v3, v3, v4, vcc
	v_add_u32_e32 v4, 1, v1
	v_cmp_ge_u32_e32 vcc, v3, v2
	v_add_u32_e32 v3, 1, v5
	s_nop 0
	v_cndmask_b32_e32 v1, v1, v4, vcc
	v_mul_lo_u32 v4, v2, v1
	v_add_u32_e32 v2, v4, v2
	v_cmp_ne_u32_e32 vcc, v3, v2
	s_and_saveexec_b64 s[6:7], vcc
	s_xor_b64 s[6:7], exec, s[6:7]
	s_cbranch_execz .LBB0_1355
	s_waitcnt lgkmcnt(0)
	v_readlane_b32 s12, v244, 6
	v_readlane_b32 s13, v244, 7
	v_mov_b32_e32 v0, 0
	s_add_u32 s12, s12, 0x1fd03500
	s_addc_u32 s13, s13, 0
	v_mov_b32_e32 v1, 2
	s_nop 0
	global_load_dword v0, v0, s[12:13] sc1
	s_waitcnt vmcnt(0)
	v_cmp_eq_u32_e32 vcc, v0, v1
	s_and_saveexec_b64 s[8:9], vcc
	s_cbranch_execz .LBB0_1354
	v_readlane_b32 s16, v244, 0
	v_readlane_b32 s17, v244, 1
	v_readlane_b32 s18, v244, 2
	v_readlane_b32 s19, v244, 3
	v_readlane_b32 s20, v244, 4
	v_readlane_b32 s21, v244, 5
	v_readlane_b32 s22, v244, 6
	v_readlane_b32 s23, v244, 7
	s_mov_b64 s[16:17], s[20:21]
	s_mov_b64 s[18:19], s[22:23]
	s_add_u32 s10, s18, 0x1fd00200
	s_addc_u32 s11, s19, 0
	s_mov_b32 s24, 1
	s_mov_b64 s[14:15], 0
	v_mov_b32_e32 v0, 0
	s_branch .LBB0_1345

.LBB0_1435:
	s_or_b64 exec, exec, s[8:9]
	v_cvt_f32_u32_e32 v4, v2
	s_waitcnt vmcnt(0)
	v_readfirstlane_b32 s6, v3
	v_sub_u32_e32 v3, 0, v2
	v_rcp_iflag_f32_e32 v4, v4
	v_add_u32_e32 v5, s6, v1
	v_mul_f32_e32 v4, 0x4f7ffffe, v4
	v_cvt_u32_f32_e32 v4, v4
	v_mul_lo_u32 v1, v3, v4
	v_mul_hi_u32 v1, v4, v1
	v_add_u32_e32 v1, v4, v1
	v_mul_hi_u32 v1, v5, v1
	v_mul_lo_u32 v3, v1, v2
	v_sub_u32_e32 v3, v5, v3
	v_add_u32_e32 v4, 1, v1
	v_cmp_ge_u32_e32 vcc, v3, v2
	s_nop 1
	v_cndmask_b32_e32 v1, v1, v4, vcc
	v_sub_u32_e32 v4, v3, v2
	v_cndmask_b32_e32 v3, v3, v4, vcc
	v_add_u32_e32 v4, 1, v1
	v_cmp_ge_u32_e32 vcc, v3, v2
	v_add_u32_e32 v3, 1, v5
	s_nop 0
	v_cndmask_b32_e32 v1, v1, v4, vcc
	v_mul_lo_u32 v4, v2, v1
	v_add_u32_e32 v2, v4, v2
	v_cmp_ne_u32_e32 vcc, v3, v2
	s_and_saveexec_b64 s[6:7], vcc
	s_xor_b64 s[6:7], exec, s[6:7]
	s_cbranch_execz .LBB0_1449
	s_waitcnt lgkmcnt(0)
	v_readlane_b32 s12, v244, 6
	v_readlane_b32 s13, v244, 7
	v_mov_b32_e32 v0, 0
	s_add_u32 s12, s12, 0x1fd03500
	s_addc_u32 s13, s13, 0
	v_mov_b32_e32 v1, 3
	s_nop 0
	global_load_dword v0, v0, s[12:13] sc1
	s_waitcnt vmcnt(0)
	v_cmp_eq_u32_e32 vcc, v0, v1
	s_and_saveexec_b64 s[8:9], vcc
	s_cbranch_execz .LBB0_1448
	v_readlane_b32 s16, v244, 0
	v_readlane_b32 s17, v244, 1
	v_readlane_b32 s18, v244, 2
	v_readlane_b32 s19, v244, 3
	v_readlane_b32 s20, v244, 4
	v_readlane_b32 s21, v244, 5
	v_readlane_b32 s22, v244, 6
	v_readlane_b32 s23, v244, 7
	s_mov_b64 s[16:17], s[20:21]
	s_mov_b64 s[18:19], s[22:23]
	s_add_u32 s10, s18, 0x1fd00200
	s_addc_u32 s11, s19, 0
	s_mov_b32 s24, 1
	s_mov_b64 s[14:15], 0
	v_mov_b32_e32 v0, 0
	s_branch .LBB0_1439

.LBB0_1531:
	s_or_b64 exec, exec, s[8:9]
	v_cvt_f32_u32_e32 v4, v2
	s_waitcnt vmcnt(0)
	v_readfirstlane_b32 s6, v3
	v_sub_u32_e32 v3, 0, v2
	v_rcp_iflag_f32_e32 v4, v4
	v_add_u32_e32 v5, s6, v1
	v_mul_f32_e32 v4, 0x4f7ffffe, v4
	v_cvt_u32_f32_e32 v4, v4
	v_mul_lo_u32 v1, v3, v4
	v_mul_hi_u32 v1, v4, v1
	v_add_u32_e32 v1, v4, v1
	v_mul_hi_u32 v1, v5, v1
	v_mul_lo_u32 v3, v1, v2
	v_sub_u32_e32 v3, v5, v3
	v_add_u32_e32 v4, 1, v1
	v_cmp_ge_u32_e32 vcc, v3, v2
	s_nop 1
	v_cndmask_b32_e32 v1, v1, v4, vcc
	v_sub_u32_e32 v4, v3, v2
	v_cndmask_b32_e32 v3, v3, v4, vcc
	v_add_u32_e32 v4, 1, v1
	v_cmp_ge_u32_e32 vcc, v3, v2
	v_add_u32_e32 v3, 1, v5
	s_nop 0
	v_cndmask_b32_e32 v1, v1, v4, vcc
	v_mul_lo_u32 v4, v2, v1
	v_add_u32_e32 v2, v4, v2
	v_cmp_ne_u32_e32 vcc, v3, v2
	s_and_saveexec_b64 s[6:7], vcc
	s_xor_b64 s[6:7], exec, s[6:7]
	s_cbranch_execz .LBB0_1545
	s_waitcnt lgkmcnt(0)
	v_readlane_b32 s12, v244, 6
	v_readlane_b32 s13, v244, 7
	v_mov_b32_e32 v0, 0
	s_add_u32 s12, s12, 0x1fd03500
	s_addc_u32 s13, s13, 0
	v_mov_b32_e32 v1, 4
	s_nop 0
	global_load_dword v0, v0, s[12:13] sc1
	s_waitcnt vmcnt(0)
	v_cmp_eq_u32_e32 vcc, v0, v1
	s_and_saveexec_b64 s[8:9], vcc
	s_cbranch_execz .LBB0_1544
	v_readlane_b32 s16, v244, 0
	v_readlane_b32 s17, v244, 1
	v_readlane_b32 s18, v244, 2
	v_readlane_b32 s19, v244, 3
	v_readlane_b32 s20, v244, 4
	v_readlane_b32 s21, v244, 5
	v_readlane_b32 s22, v244, 6
	v_readlane_b32 s23, v244, 7
	s_mov_b64 s[16:17], s[20:21]
	s_mov_b64 s[18:19], s[22:23]
	s_add_u32 s10, s18, 0x1fd00200
	s_addc_u32 s11, s19, 0
	s_mov_b32 s24, 1
	s_mov_b64 s[14:15], 0
	v_mov_b32_e32 v0, 0
	s_branch .LBB0_1535

.LBB0_1734:
	s_or_b64 exec, exec, s[8:9]
	v_cvt_f32_u32_e32 v4, v2
	s_waitcnt vmcnt(0)
	v_readfirstlane_b32 s6, v3
	v_sub_u32_e32 v3, 0, v2
	v_rcp_iflag_f32_e32 v4, v4
	v_add_u32_e32 v5, s6, v1
	v_mul_f32_e32 v4, 0x4f7ffffe, v4
	v_cvt_u32_f32_e32 v4, v4
	v_mul_lo_u32 v1, v3, v4
	v_mul_hi_u32 v1, v4, v1
	v_add_u32_e32 v1, v4, v1
	v_mul_hi_u32 v1, v5, v1
	v_mul_lo_u32 v3, v1, v2
	v_sub_u32_e32 v3, v5, v3
	v_add_u32_e32 v4, 1, v1
	v_cmp_ge_u32_e32 vcc, v3, v2
	s_nop 1
	v_cndmask_b32_e32 v1, v1, v4, vcc
	v_sub_u32_e32 v4, v3, v2
	v_cndmask_b32_e32 v3, v3, v4, vcc
	v_add_u32_e32 v4, 1, v1
	v_cmp_ge_u32_e32 vcc, v3, v2
	v_add_u32_e32 v3, 1, v5
	s_nop 0
	v_cndmask_b32_e32 v1, v1, v4, vcc
	v_mul_lo_u32 v4, v2, v1
	v_add_u32_e32 v2, v4, v2
	v_cmp_ne_u32_e32 vcc, v3, v2
	s_and_saveexec_b64 s[6:7], vcc
	s_xor_b64 s[6:7], exec, s[6:7]
	s_cbranch_execz .LBB0_1748
	s_waitcnt lgkmcnt(0)
	v_readlane_b32 s12, v244, 6
	v_readlane_b32 s13, v244, 7
	v_mov_b32_e32 v0, 0
	s_add_u32 s12, s12, 0x1fd03500
	s_addc_u32 s13, s13, 0
	v_mov_b32_e32 v1, 5
	s_nop 0
	global_load_dword v0, v0, s[12:13] sc1
	s_waitcnt vmcnt(0)
	v_cmp_eq_u32_e32 vcc, v0, v1
	s_and_saveexec_b64 s[8:9], vcc
	s_cbranch_execz .LBB0_1747
	v_readlane_b32 s16, v244, 0
	v_readlane_b32 s17, v244, 1
	v_readlane_b32 s18, v244, 2
	v_readlane_b32 s19, v244, 3
	v_readlane_b32 s20, v244, 4
	v_readlane_b32 s21, v244, 5
	v_readlane_b32 s22, v244, 6
	v_readlane_b32 s23, v244, 7
	s_mov_b64 s[16:17], s[20:21]
	s_mov_b64 s[18:19], s[22:23]
	s_add_u32 s10, s18, 0x1fd00200
	s_addc_u32 s11, s19, 0
	s_mov_b32 s24, 1
	s_mov_b64 s[14:15], 0
	v_mov_b32_e32 v0, 0
	s_branch .LBB0_1738
